# v30 with the barrier-entry L1 invalidate issued by wave 7 (usually the first wave to finish a phase) instead of wave 0
# speedup vs baseline: 1.0199x; 1.0152x over previous
; __device__ __forceinline__ void xcd_barrier(const XcdBarrier& b) {
;     asm volatile("s_waitcnt vmcnt(0)" ::: "memory");
;     __syncthreads();
;     int tid0 = threadIdx.x; asm volatile("" : "+v"(tid0));
;     if (tid0 == 0) {
.LBB0_103:
	s_getreg_b32 s0, hwreg(HW_REG_XCC_ID, 0, 4)
	s_cselect_b32 s99, 1, 0
	v_readfirstlane_b32 s98, v217
	s_cmp_lt_u32 s98, 0x1c0
	s_cbranch_scc1 .Lxb_noinv_1
	buffer_inv sc1

; __device__ __forceinline__ void xcd_barrier(const XcdBarrier& b) {
;     asm volatile("s_waitcnt vmcnt(0)" ::: "memory");
;     __syncthreads();
;     int tid0 = threadIdx.x; asm volatile("" : "+v"(tid0));
;     if (tid0 == 0) {
.LBB0_186:
	s_mov_b64 s[4:5], 0
	s_getreg_b32 s6, hwreg(HW_REG_XCC_ID, 0, 4)
	s_cselect_b32 s99, 1, 0
	v_readfirstlane_b32 s98, v217
	s_cmp_lt_u32 s98, 0x1c0
	s_cbranch_scc1 .Lxb_noinv_2
	buffer_inv sc1

; __device__ __forceinline__ void xcd_barrier(const XcdBarrier& b) {
;     asm volatile("s_waitcnt vmcnt(0)" ::: "memory");
;     __syncthreads();
;     int tid0 = threadIdx.x; asm volatile("" : "+v"(tid0));
;     if (tid0 == 0) {
.LBB0_283:
	s_waitcnt lgkmcnt(0)
	s_mov_b64 s[4:5], 0
	s_getreg_b32 s6, hwreg(HW_REG_XCC_ID, 0, 4)
	s_cselect_b32 s99, 1, 0
	v_readfirstlane_b32 s98, v217
	s_cmp_lt_u32 s98, 0x1c0
	s_cbranch_scc1 .Lxb_noinv_3
	buffer_inv sc1
